# GEMM k-loop: fragment ds_reads issued before the LDS-DMA block (scalar-address form), so LDS latency overlaps DMA issue
# speedup vs baseline: 1.0148x; 1.0127x over previous
; template <int EPI>
; __device__ __forceinline__ void gemm_phase(const u16* __restrict__ A0, int nksA, size_t sA, const u16* __restrict__ B0, int nksB, size_t sB,
;                                            int K, int nM, int nN, int nbatch, const EpiArgs ea, char* smem, int bid, int nblk) {
;     ...
;     for (int kk = 0; kk < nk; ++kk) {
;       const bool more = kk + 2 < nk;
;       if (more) GSTAGE(kk + 2, nbuf);
;       bf16x8 Bl[4], At[8];
;       {
;         const int bb = sb0 + buf * 8192, ab = sa0 + buf * 16384;
;         asm volatile(
;             "ds_read_b128 %0, %12\n\tds_read_b128 %1, %12 offset:1024\n\tds_read_b128 %2, %12 offset:2048\n\tds_read_b128 %3, %12 offset:3072\n\t"
;             "ds_read_b128 %4, %13\n\tds_read_b128 %5, %13 offset:1024\n\tds_read_b128 %6, %13 offset:2048\n\tds_read_b128 %7, %13 offset:3072\n\t"
;             "ds_read_b128 %8, %13 offset:4096\n\tds_read_b128 %9, %13 offset:5120\n\tds_read_b128 %10, %13 offset:6144\n\tds_read_b128 %11, %13 offset:7168\n\t"
;             "s_waitcnt lgkmcnt(4)"
;             : "=&v"(Bl[0]), "=&v"(Bl[1]), "=&v"(Bl[2]), "=&v"(Bl[3]), "=&v"(At[0]), "=&v"(At[1]), "=&v"(At[2]), "=&v"(At[3]),
;               "=&v"(At[4]), "=&v"(At[5]), "=&v"(At[6]), "=&v"(At[7])
;             : "v"(bb), "v"(ab)
;             : "memory");
;       }
.LBB0_183:
	v_lshl_add_u32 v134, s89, 13, v148
	v_lshl_add_u32 v165, s89, 14, v147
	ds_read_b128 v[136:139], v134
	ds_read_b128 v[140:143], v134 offset:1024
	ds_read_b128 v[166:169], v134 offset:2048
	ds_read_b128 v[170:173], v134 offset:3072
	ds_read_b128 v[174:177], v165
	ds_read_b128 v[178:181], v165 offset:1024
	ds_read_b128 v[182:185], v165 offset:2048
	ds_read_b128 v[186:189], v165 offset:3072
	ds_read_b128 v[190:193], v165 offset:4096
	ds_read_b128 v[194:197], v165 offset:5120
	ds_read_b128 v[200:203], v165 offset:6144
	ds_read_b128 v[204:207], v165 offset:7168
	s_cbranch_vccnz .Lgd0_skip
	v_readfirstlane_b32 s93, v128
	v_add_u32_e32 v245, 0x1000, v128
	v_add_u32_e32 v246, 0x2000, v128
	v_add_u32_e32 v247, 0x3000, v128
	s_lshl_b32 s92, s31, 14
	s_add_u32 s92, s92, s93
	s_add_u32 s94, s58, 0x31b8000
	s_addc_u32 s95, s59, 0
	s_mov_b32 m0, s92
	s_add_u32 s100, s56, 0x4000
	s_addc_u32 s101, s57, 0
	global_load_lds_dwordx4 v128, s[94:95]
	s_add_u32 m0, s92, 0x1000
	s_lshl_b32 s98, s31, 13
	global_load_lds_dwordx4 v245, s[94:95]
	s_add_u32 m0, s92, 0x2000
	s_add_u32 s98, s98, s93
	global_load_lds_dwordx4 v246, s[94:95]
	s_add_u32 m0, s92, 0x3000
	s_add_u32 s98, s98, 0xc000
	global_load_lds_dwordx4 v247, s[94:95]
	s_mov_b32 m0, s98
	s_nop 0
	global_load_lds_dwordx4 v128, s[100:101]
	s_add_u32 m0, s98, 0x1000
	s_nop 0
	global_load_lds_dwordx4 v245, s[100:101]
.Lgd0_skip:
	s_waitcnt lgkmcnt(7)
	s_setprio 1
	v_mfma_f32_16x16x32_bf16 v[124:127], v[136:139], v[174:177], v[124:127]
	v_mfma_f32_16x16x32_bf16 v[120:123], v[140:143], v[174:177], v[120:123]
	v_mfma_f32_16x16x32_bf16 v[116:119], v[166:169], v[174:177], v[116:119]
	v_mfma_f32_16x16x32_bf16 v[112:115], v[170:173], v[174:177], v[112:115]
	s_waitcnt lgkmcnt(6)
	v_mfma_f32_16x16x32_bf16 v[108:111], v[136:139], v[178:181], v[108:111]
	v_mfma_f32_16x16x32_bf16 v[104:107], v[140:143], v[178:181], v[104:107]
	v_mfma_f32_16x16x32_bf16 v[100:103], v[166:169], v[178:181], v[100:103]
	v_mfma_f32_16x16x32_bf16 v[96:99], v[170:173], v[178:181], v[96:99]
	s_waitcnt lgkmcnt(5)
	v_mfma_f32_16x16x32_bf16 v[92:95], v[136:139], v[182:185], v[92:95]
	v_mfma_f32_16x16x32_bf16 v[88:91], v[140:143], v[182:185], v[88:91]
	v_mfma_f32_16x16x32_bf16 v[84:87], v[166:169], v[182:185], v[84:87]
	v_mfma_f32_16x16x32_bf16 v[80:83], v[170:173], v[182:185], v[80:83]
	s_waitcnt lgkmcnt(4)
	v_mfma_f32_16x16x32_bf16 v[76:79], v[136:139], v[186:189], v[76:79]
	v_mfma_f32_16x16x32_bf16 v[72:75], v[140:143], v[186:189], v[72:75]
	v_mfma_f32_16x16x32_bf16 v[68:71], v[166:169], v[186:189], v[68:71]
	v_mfma_f32_16x16x32_bf16 v[64:67], v[170:173], v[186:189], v[64:67]
	s_waitcnt lgkmcnt(3)
	s_nop 0
	v_mfma_f32_16x16x32_bf16 v[60:63], v[136:139], v[190:193], v[60:63]
	v_mfma_f32_16x16x32_bf16 v[56:59], v[140:143], v[190:193], v[56:59]
	v_mfma_f32_16x16x32_bf16 v[52:55], v[166:169], v[190:193], v[52:55]
	v_mfma_f32_16x16x32_bf16 v[48:51], v[170:173], v[190:193], v[48:51]
	s_waitcnt lgkmcnt(2)
	v_mfma_f32_16x16x32_bf16 v[44:47], v[136:139], v[194:197], v[44:47]
	v_mfma_f32_16x16x32_bf16 v[40:43], v[140:143], v[194:197], v[40:43]
	v_mfma_f32_16x16x32_bf16 v[36:39], v[166:169], v[194:197], v[36:39]
	v_mfma_f32_16x16x32_bf16 v[32:35], v[170:173], v[194:197], v[32:35]
	s_waitcnt lgkmcnt(1)
	v_mfma_f32_16x16x32_bf16 v[28:31], v[136:139], v[200:203], v[28:31]
	v_mfma_f32_16x16x32_bf16 v[24:27], v[140:143], v[200:203], v[24:27]
	v_mfma_f32_16x16x32_bf16 v[16:19], v[166:169], v[200:203], v[16:19]
	v_mfma_f32_16x16x32_bf16 v[4:7], v[170:173], v[200:203], v[4:7]
	s_waitcnt lgkmcnt(0)
	v_mfma_f32_16x16x32_bf16 v[20:23], v[136:139], v[204:207], v[20:23]
	v_mfma_f32_16x16x32_bf16 v[12:15], v[140:143], v[204:207], v[12:15]
	v_mfma_f32_16x16x32_bf16 v[8:11], v[166:169], v[204:207], v[8:11]
	v_mfma_f32_16x16x32_bf16 v[0:3], v[170:173], v[204:207], v[0:3]
	s_setprio 0
	s_and_b64 vcc, exec, s[64:65]
	s_cbranch_vccnz .Lgt0_last
	s_add_i32 s36, s89, 1
	s_cmp_lg_u32 s89, 2
	s_cselect_b32 s89, s36, 0
	s_add_i32 s36, s31, 1
	s_cmp_lg_u32 s31, 2
	s_cselect_b32 s31, s36, 0
	s_add_i32 s5, s5, 1
	s_add_u32 s56, s56, 0x2000
	s_addc_u32 s57, s57, 0
	s_add_u32 s58, s58, 0x4000
	s_addc_u32 s59, s59, 0
	s_cmp_eq_u32 s5, 32
	s_waitcnt vmcnt(6)
	s_barrier
	s_branch .LBB0_181

; template <int EPI>
; __device__ __forceinline__ void gemm_phase(const u16* __restrict__ A0, int nksA, size_t sA, const u16* __restrict__ B0, int nksB, size_t sB,
;                                            int K, int nM, int nN, int nbatch, const EpiArgs ea, char* smem, int bid, int nblk) {
;     ...
;     for (int kk = 0; kk < nk; ++kk) {
;       const bool more = kk + 2 < nk;
;       if (more) GSTAGE(kk + 2, nbuf);
;       bf16x8 Bl[4], At[8];
;       {
;         const int bb = sb0 + buf * 8192, ab = sa0 + buf * 16384;
;         asm volatile(
;             "ds_read_b128 %0, %12\n\tds_read_b128 %1, %12 offset:1024\n\tds_read_b128 %2, %12 offset:2048\n\tds_read_b128 %3, %12 offset:3072\n\t"
;             "ds_read_b128 %4, %13\n\tds_read_b128 %5, %13 offset:1024\n\tds_read_b128 %6, %13 offset:2048\n\tds_read_b128 %7, %13 offset:3072\n\t"
;             "ds_read_b128 %8, %13 offset:4096\n\tds_read_b128 %9, %13 offset:5120\n\tds_read_b128 %10, %13 offset:6144\n\tds_read_b128 %11, %13 offset:7168\n\t"
;             "s_waitcnt lgkmcnt(4)"
;             : "=&v"(Bl[0]), "=&v"(Bl[1]), "=&v"(Bl[2]), "=&v"(Bl[3]), "=&v"(At[0]), "=&v"(At[1]), "=&v"(At[2]), "=&v"(At[3]),
;               "=&v"(At[4]), "=&v"(At[5]), "=&v"(At[6]), "=&v"(At[7])
;             : "v"(bb), "v"(ab)
;             : "memory");
;       }
.LBB0_386:
	v_lshl_add_u32 v196, s90, 13, v135
	v_lshl_add_u32 v197, s90, 14, v134
	ds_read_b128 v[148:151], v196
	ds_read_b128 v[152:155], v196 offset:1024
	ds_read_b128 v[156:159], v196 offset:2048
	ds_read_b128 v[160:163], v196 offset:3072
	ds_read_b128 v[164:167], v197
	ds_read_b128 v[168:171], v197 offset:1024
	ds_read_b128 v[172:175], v197 offset:2048
	ds_read_b128 v[176:179], v197 offset:3072
	ds_read_b128 v[180:183], v197 offset:4096
	ds_read_b128 v[184:187], v197 offset:5120
	ds_read_b128 v[188:191], v197 offset:6144
	ds_read_b128 v[192:195], v197 offset:7168
	s_cbranch_vccnz .Lgd1_skip
	v_readfirstlane_b32 s93, v128
	v_add_u32_e32 v245, 0x1000, v128
	v_add_u32_e32 v246, 0x2000, v128
	v_add_u32_e32 v247, 0x3000, v128
	s_lshl_b32 s92, s87, 14
	s_add_u32 s92, s92, s93
	s_add_u32 s94, s66, 0x91b8000
	s_addc_u32 s95, s67, 0
	s_mov_b32 m0, s92
	s_add_u32 s100, s64, 0xcdb4000
	s_addc_u32 s101, s65, 0
	global_load_lds_dwordx4 v128, s[94:95]
	s_add_u32 m0, s92, 0x1000
	s_lshl_b32 s98, s87, 13
	global_load_lds_dwordx4 v245, s[94:95]
	s_add_u32 m0, s92, 0x2000
	s_add_u32 s98, s98, s93
	global_load_lds_dwordx4 v246, s[94:95]
	s_add_u32 m0, s92, 0x3000
	s_add_u32 s98, s98, 0xc000
	global_load_lds_dwordx4 v247, s[94:95]
	s_mov_b32 m0, s98
	s_nop 0
	global_load_lds_dwordx4 v128, s[100:101]
	s_add_u32 m0, s98, 0x1000
	s_nop 0
	global_load_lds_dwordx4 v245, s[100:101]
.Lgd1_skip:
	s_waitcnt lgkmcnt(7)
	s_setprio 1
	v_mfma_f32_16x16x32_bf16 v[124:127], v[148:151], v[164:167], v[124:127]
	v_mfma_f32_16x16x32_bf16 v[120:123], v[152:155], v[164:167], v[120:123]
	v_mfma_f32_16x16x32_bf16 v[116:119], v[156:159], v[164:167], v[116:119]
	v_mfma_f32_16x16x32_bf16 v[112:115], v[160:163], v[164:167], v[112:115]
	s_waitcnt lgkmcnt(6)
	v_mfma_f32_16x16x32_bf16 v[108:111], v[148:151], v[168:171], v[108:111]
	v_mfma_f32_16x16x32_bf16 v[104:107], v[152:155], v[168:171], v[104:107]
	v_mfma_f32_16x16x32_bf16 v[100:103], v[156:159], v[168:171], v[100:103]
	v_mfma_f32_16x16x32_bf16 v[96:99], v[160:163], v[168:171], v[96:99]
	s_waitcnt lgkmcnt(5)
	v_mfma_f32_16x16x32_bf16 v[92:95], v[148:151], v[172:175], v[92:95]
	v_mfma_f32_16x16x32_bf16 v[88:91], v[152:155], v[172:175], v[88:91]
	v_mfma_f32_16x16x32_bf16 v[80:83], v[156:159], v[172:175], v[80:83]
	v_mfma_f32_16x16x32_bf16 v[72:75], v[160:163], v[172:175], v[72:75]
	s_waitcnt lgkmcnt(4)
	v_mfma_f32_16x16x32_bf16 v[60:63], v[148:151], v[176:179], v[60:63]
	v_mfma_f32_16x16x32_bf16 v[56:59], v[152:155], v[176:179], v[56:59]
	v_mfma_f32_16x16x32_bf16 v[52:55], v[156:159], v[176:179], v[52:55]
	v_mfma_f32_16x16x32_bf16 v[48:51], v[160:163], v[176:179], v[48:51]
	s_waitcnt lgkmcnt(3)
	s_nop 0
	v_mfma_f32_16x16x32_bf16 v[44:47], v[148:151], v[180:183], v[44:47]
	v_mfma_f32_16x16x32_bf16 v[40:43], v[152:155], v[180:183], v[40:43]
	v_mfma_f32_16x16x32_bf16 v[36:39], v[156:159], v[180:183], v[36:39]
	v_mfma_f32_16x16x32_bf16 v[32:35], v[160:163], v[180:183], v[32:35]
	s_waitcnt lgkmcnt(2)
	v_mfma_f32_16x16x32_bf16 v[28:31], v[148:151], v[184:187], v[28:31]
	v_mfma_f32_16x16x32_bf16 v[24:27], v[152:155], v[184:187], v[24:27]
	v_mfma_f32_16x16x32_bf16 v[20:23], v[156:159], v[184:187], v[20:23]
	v_mfma_f32_16x16x32_bf16 v[16:19], v[160:163], v[184:187], v[16:19]
	s_waitcnt lgkmcnt(1)
	v_mfma_f32_16x16x32_bf16 v[12:15], v[148:151], v[188:191], v[12:15]
	v_mfma_f32_16x16x32_bf16 v[8:11], v[152:155], v[188:191], v[8:11]
	v_mfma_f32_16x16x32_bf16 v[4:7], v[156:159], v[188:191], v[4:7]
	v_mfma_f32_16x16x32_bf16 v[0:3], v[160:163], v[188:191], v[0:3]
	s_waitcnt lgkmcnt(0)
	v_mfma_f32_16x16x32_bf16 v[64:67], v[148:151], v[192:195], v[64:67]
	v_mfma_f32_16x16x32_bf16 v[68:71], v[152:155], v[192:195], v[68:71]
	v_mfma_f32_16x16x32_bf16 v[76:79], v[156:159], v[192:195], v[76:79]
	v_mfma_f32_16x16x32_bf16 v[84:87], v[160:163], v[192:195], v[84:87]
	s_setprio 0
	s_and_b64 vcc, exec, s[80:81]
	s_cbranch_vccnz .Lgt1_last
	s_add_i32 s36, s90, 1
	s_cmp_lg_u32 s90, 2
	s_cselect_b32 s90, s36, 0
	s_add_i32 s36, s87, 1
	s_cmp_lg_u32 s87, 2
	s_cselect_b32 s87, s36, 0
	s_add_i32 s89, s89, 1
	s_add_u32 s64, s64, 0x2000
	s_addc_u32 s65, s65, 0
	s_add_u32 s66, s66, 0x4000
	s_addc_u32 s67, s67, 0
	s_cmp_eq_u32 s89, 16
	s_waitcnt vmcnt(6)
	s_barrier
	s_branch .LBB0_384

; template <int EPI>
; __device__ __forceinline__ void gemm_phase(const u16* __restrict__ A0, int nksA, size_t sA, const u16* __restrict__ B0, int nksB, size_t sB,
;                                            int K, int nM, int nN, int nbatch, const EpiArgs ea, char* smem, int bid, int nblk) {
;     ...
;     for (int kk = 0; kk < nk; ++kk) {
;       const bool more = kk + 2 < nk;
;       if (more) GSTAGE(kk + 2, nbuf);
;       bf16x8 Bl[4], At[8];
;       {
;         const int bb = sb0 + buf * 8192, ab = sa0 + buf * 16384;
;         asm volatile(
;             "ds_read_b128 %0, %12\n\tds_read_b128 %1, %12 offset:1024\n\tds_read_b128 %2, %12 offset:2048\n\tds_read_b128 %3, %12 offset:3072\n\t"
;             "ds_read_b128 %4, %13\n\tds_read_b128 %5, %13 offset:1024\n\tds_read_b128 %6, %13 offset:2048\n\tds_read_b128 %7, %13 offset:3072\n\t"
;             "ds_read_b128 %8, %13 offset:4096\n\tds_read_b128 %9, %13 offset:5120\n\tds_read_b128 %10, %13 offset:6144\n\tds_read_b128 %11, %13 offset:7168\n\t"
;             "s_waitcnt lgkmcnt(4)"
;             : "=&v"(Bl[0]), "=&v"(Bl[1]), "=&v"(Bl[2]), "=&v"(Bl[3]), "=&v"(At[0]), "=&v"(At[1]), "=&v"(At[2]), "=&v"(At[3]),
;               "=&v"(At[4]), "=&v"(At[5]), "=&v"(At[6]), "=&v"(At[7])
;             : "v"(bb), "v"(ab)
;             : "memory");
;       }
.LBB0_1281:
	v_lshl_add_u32 v147, s43, 13, v183
	v_lshl_add_u32 v149, s43, 14, v182
	ds_read_b128 v[154:157], v147
	ds_read_b128 v[158:161], v147 offset:1024
	ds_read_b128 v[162:165], v147 offset:2048
	ds_read_b128 v[166:169], v147 offset:3072
	ds_read_b128 v[170:173], v149
	ds_read_b128 v[174:177], v149 offset:1024
	ds_read_b128 v[200:203], v149 offset:2048
	ds_read_b128 v[204:207], v149 offset:3072
	ds_read_b128 v[208:211], v149 offset:4096
	ds_read_b128 v[212:215], v149 offset:5120
	ds_read_b128 v[216:219], v149 offset:6144
	ds_read_b128 v[220:223], v149 offset:7168
	s_cbranch_vccnz .Lgd2_skip
	v_readfirstlane_b32 s93, v128
	v_add_u32_e32 v245, 0x1000, v128
	v_add_u32_e32 v246, 0x2000, v128
	v_add_u32_e32 v247, 0x3000, v128
	s_lshl_b32 s92, s35, 14
	s_add_u32 s92, s92, s93
	s_add_u32 s94, s52, 0x71b8000
	s_addc_u32 s95, s53, 0
	s_mov_b32 m0, s92
	s_add_u32 s100, s50, 0x704000
	s_addc_u32 s101, s51, 0
	global_load_lds_dwordx4 v128, s[94:95]
	s_add_u32 m0, s92, 0x1000
	s_lshl_b32 s98, s35, 13
	global_load_lds_dwordx4 v245, s[94:95]
	s_add_u32 m0, s92, 0x2000
	s_add_u32 s98, s98, s93
	global_load_lds_dwordx4 v246, s[94:95]
	s_add_u32 m0, s92, 0x3000
	s_add_u32 s98, s98, 0xc000
	global_load_lds_dwordx4 v247, s[94:95]
	s_mov_b32 m0, s98
	s_nop 0
	global_load_lds_dwordx4 v128, s[100:101]
	s_add_u32 m0, s98, 0x1000
	s_nop 0
	global_load_lds_dwordx4 v245, s[100:101]
.Lgd2_skip:
	s_waitcnt lgkmcnt(7)
	s_setprio 1
	v_mfma_f32_16x16x32_bf16 v[124:127], v[154:157], v[170:173], v[124:127]
	v_mfma_f32_16x16x32_bf16 v[120:123], v[158:161], v[170:173], v[120:123]
	v_mfma_f32_16x16x32_bf16 v[116:119], v[162:165], v[170:173], v[116:119]
	v_mfma_f32_16x16x32_bf16 v[112:115], v[166:169], v[170:173], v[112:115]
	s_waitcnt lgkmcnt(6)
	v_mfma_f32_16x16x32_bf16 v[108:111], v[154:157], v[174:177], v[108:111]
	v_mfma_f32_16x16x32_bf16 v[104:107], v[158:161], v[174:177], v[104:107]
	v_mfma_f32_16x16x32_bf16 v[100:103], v[162:165], v[174:177], v[100:103]
	v_mfma_f32_16x16x32_bf16 v[96:99], v[166:169], v[174:177], v[96:99]
	s_waitcnt lgkmcnt(5)
	v_mfma_f32_16x16x32_bf16 v[92:95], v[154:157], v[200:203], v[92:95]
	v_mfma_f32_16x16x32_bf16 v[88:91], v[158:161], v[200:203], v[88:91]
	v_mfma_f32_16x16x32_bf16 v[84:87], v[162:165], v[200:203], v[84:87]
	v_mfma_f32_16x16x32_bf16 v[80:83], v[166:169], v[200:203], v[80:83]
	s_waitcnt lgkmcnt(4)
	v_mfma_f32_16x16x32_bf16 v[76:79], v[154:157], v[204:207], v[76:79]
	v_mfma_f32_16x16x32_bf16 v[72:75], v[158:161], v[204:207], v[72:75]
	v_mfma_f32_16x16x32_bf16 v[68:71], v[162:165], v[204:207], v[68:71]
	v_mfma_f32_16x16x32_bf16 v[64:67], v[166:169], v[204:207], v[64:67]
	s_waitcnt lgkmcnt(3)
	s_nop 0
	v_mfma_f32_16x16x32_bf16 v[60:63], v[154:157], v[208:211], v[60:63]
	v_mfma_f32_16x16x32_bf16 v[56:59], v[158:161], v[208:211], v[56:59]
	v_mfma_f32_16x16x32_bf16 v[52:55], v[162:165], v[208:211], v[52:55]
	v_mfma_f32_16x16x32_bf16 v[48:51], v[166:169], v[208:211], v[48:51]
	s_waitcnt lgkmcnt(2)
	v_mfma_f32_16x16x32_bf16 v[44:47], v[154:157], v[212:215], v[44:47]
	v_mfma_f32_16x16x32_bf16 v[40:43], v[158:161], v[212:215], v[40:43]
	v_mfma_f32_16x16x32_bf16 v[36:39], v[162:165], v[212:215], v[36:39]
	v_mfma_f32_16x16x32_bf16 v[32:35], v[166:169], v[212:215], v[32:35]
	s_waitcnt lgkmcnt(1)
	v_mfma_f32_16x16x32_bf16 v[28:31], v[154:157], v[216:219], v[28:31]
	v_mfma_f32_16x16x32_bf16 v[24:27], v[158:161], v[216:219], v[24:27]
	v_mfma_f32_16x16x32_bf16 v[20:23], v[162:165], v[216:219], v[20:23]
	v_mfma_f32_16x16x32_bf16 v[12:15], v[166:169], v[216:219], v[12:15]
	s_waitcnt lgkmcnt(0)
	v_mfma_f32_16x16x32_bf16 v[16:19], v[154:157], v[220:223], v[16:19]
	v_mfma_f32_16x16x32_bf16 v[8:11], v[158:161], v[220:223], v[8:11]
	v_mfma_f32_16x16x32_bf16 v[4:7], v[162:165], v[220:223], v[4:7]
	v_mfma_f32_16x16x32_bf16 v[0:3], v[166:169], v[220:223], v[0:3]
	s_setprio 0
	s_and_b64 vcc, exec, s[54:55]
	s_cbranch_vccnz .Lgt3_last
	s_add_i32 s36, s43, 1
	s_cmp_lg_u32 s43, 2
	s_cselect_b32 s43, s36, 0
	s_add_i32 s36, s35, 1
	s_cmp_lg_u32 s35, 2
	s_cselect_b32 s35, s36, 0
	s_add_i32 s49, s49, 1
	s_add_u32 s50, s50, 0x2000
	s_addc_u32 s51, s51, 0
	s_add_u32 s52, s52, 0x4000
	s_addc_u32 s53, s53, 0
	s_cmp_eq_u32 s49, 16
	s_waitcnt vmcnt(6)
	s_barrier
	s_branch .LBB0_1279

; template <int EPI>
; __device__ __forceinline__ void gemm_phase(const u16* __restrict__ A0, int nksA, size_t sA, const u16* __restrict__ B0, int nksB, size_t sB,
;                                            int K, int nM, int nN, int nbatch, const EpiArgs ea, char* smem, int bid, int nblk) {
;     ...
;     for (int kk = 0; kk < nk; ++kk) {
;       const bool more = kk + 2 < nk;
;       if (more) GSTAGE(kk + 2, nbuf);
;       bf16x8 Bl[4], At[8];
;       {
;         const int bb = sb0 + buf * 8192, ab = sa0 + buf * 16384;
;         asm volatile(
;             "ds_read_b128 %0, %12\n\tds_read_b128 %1, %12 offset:1024\n\tds_read_b128 %2, %12 offset:2048\n\tds_read_b128 %3, %12 offset:3072\n\t"
;             "ds_read_b128 %4, %13\n\tds_read_b128 %5, %13 offset:1024\n\tds_read_b128 %6, %13 offset:2048\n\tds_read_b128 %7, %13 offset:3072\n\t"
;             "ds_read_b128 %8, %13 offset:4096\n\tds_read_b128 %9, %13 offset:5120\n\tds_read_b128 %10, %13 offset:6144\n\tds_read_b128 %11, %13 offset:7168\n\t"
;             "s_waitcnt lgkmcnt(4)"
;             : "=&v"(Bl[0]), "=&v"(Bl[1]), "=&v"(Bl[2]), "=&v"(Bl[3]), "=&v"(At[0]), "=&v"(At[1]), "=&v"(At[2]), "=&v"(At[3]),
;               "=&v"(At[4]), "=&v"(At[5]), "=&v"(At[6]), "=&v"(At[7])
;             : "v"(bb), "v"(ab)
;             : "memory");
;       }
.LBB0_1356:
	v_lshl_add_u32 v138, s43, 13, v143
	v_lshl_add_u32 v139, s43, 14, v142
	ds_read_b128 v[134:137], v138
	ds_read_b128 v[156:159], v138 offset:1024
	ds_read_b128 v[160:163], v138 offset:2048
	ds_read_b128 v[164:167], v138 offset:3072
	ds_read_b128 v[168:171], v139
	ds_read_b128 v[172:175], v139 offset:1024
	ds_read_b128 v[176:179], v139 offset:2048
	ds_read_b128 v[180:183], v139 offset:3072
	ds_read_b128 v[184:187], v139 offset:4096
	ds_read_b128 v[188:191], v139 offset:5120
	ds_read_b128 v[192:195], v139 offset:6144
	ds_read_b128 v[200:203], v139 offset:7168
	s_cbranch_vccnz .Lgd3_skip
	v_readfirstlane_b32 s93, v128
	v_add_u32_e32 v245, 0x1000, v128
	v_add_u32_e32 v246, 0x2000, v128
	v_add_u32_e32 v247, 0x3000, v128
	s_lshl_b32 s92, s41, 14
	s_add_u32 s92, s92, s93
	s_add_u32 s94, s50, 0x31b8000
	s_addc_u32 s95, s51, 0
	s_mov_b32 m0, s92
	s_add_u32 s100, s48, 0x504000
	s_addc_u32 s101, s49, 0
	global_load_lds_dwordx4 v128, s[94:95]
	s_add_u32 m0, s92, 0x1000
	s_lshl_b32 s98, s41, 13
	global_load_lds_dwordx4 v245, s[94:95]
	s_add_u32 m0, s92, 0x2000
	s_add_u32 s98, s98, s93
	global_load_lds_dwordx4 v246, s[94:95]
	s_add_u32 m0, s92, 0x3000
	s_add_u32 s98, s98, 0xc000
	global_load_lds_dwordx4 v247, s[94:95]
	s_mov_b32 m0, s98
	s_nop 0
	global_load_lds_dwordx4 v128, s[100:101]
	s_add_u32 m0, s98, 0x1000
	s_nop 0
	global_load_lds_dwordx4 v245, s[100:101]
.Lgd3_skip:
	s_waitcnt lgkmcnt(7)
	s_setprio 1
	v_mfma_f32_16x16x32_bf16 v[124:127], v[134:137], v[168:171], v[124:127]
	v_mfma_f32_16x16x32_bf16 v[120:123], v[156:159], v[168:171], v[120:123]
	v_mfma_f32_16x16x32_bf16 v[116:119], v[160:163], v[168:171], v[116:119]
	v_mfma_f32_16x16x32_bf16 v[112:115], v[164:167], v[168:171], v[112:115]
	s_waitcnt lgkmcnt(6)
	v_mfma_f32_16x16x32_bf16 v[108:111], v[134:137], v[172:175], v[108:111]
	v_mfma_f32_16x16x32_bf16 v[104:107], v[156:159], v[172:175], v[104:107]
	v_mfma_f32_16x16x32_bf16 v[100:103], v[160:163], v[172:175], v[100:103]
	v_mfma_f32_16x16x32_bf16 v[96:99], v[164:167], v[172:175], v[96:99]
	s_waitcnt lgkmcnt(5)
	v_mfma_f32_16x16x32_bf16 v[92:95], v[134:137], v[176:179], v[92:95]
	v_mfma_f32_16x16x32_bf16 v[88:91], v[156:159], v[176:179], v[88:91]
	v_mfma_f32_16x16x32_bf16 v[84:87], v[160:163], v[176:179], v[84:87]
	v_mfma_f32_16x16x32_bf16 v[80:83], v[164:167], v[176:179], v[80:83]
	s_waitcnt lgkmcnt(4)
	v_mfma_f32_16x16x32_bf16 v[76:79], v[134:137], v[180:183], v[76:79]
	v_mfma_f32_16x16x32_bf16 v[72:75], v[156:159], v[180:183], v[72:75]
	v_mfma_f32_16x16x32_bf16 v[68:71], v[160:163], v[180:183], v[68:71]
	v_mfma_f32_16x16x32_bf16 v[64:67], v[164:167], v[180:183], v[64:67]
	s_waitcnt lgkmcnt(3)
	s_nop 0
	v_mfma_f32_16x16x32_bf16 v[60:63], v[134:137], v[184:187], v[60:63]
	v_mfma_f32_16x16x32_bf16 v[56:59], v[156:159], v[184:187], v[56:59]
	v_mfma_f32_16x16x32_bf16 v[52:55], v[160:163], v[184:187], v[52:55]
	v_mfma_f32_16x16x32_bf16 v[48:51], v[164:167], v[184:187], v[48:51]
	s_waitcnt lgkmcnt(2)
	v_mfma_f32_16x16x32_bf16 v[44:47], v[134:137], v[188:191], v[44:47]
	v_mfma_f32_16x16x32_bf16 v[40:43], v[156:159], v[188:191], v[40:43]
	v_mfma_f32_16x16x32_bf16 v[36:39], v[160:163], v[188:191], v[36:39]
	v_mfma_f32_16x16x32_bf16 v[28:31], v[164:167], v[188:191], v[28:31]
	s_waitcnt lgkmcnt(1)
	v_mfma_f32_16x16x32_bf16 v[16:19], v[134:137], v[192:195], v[16:19]
	v_mfma_f32_16x16x32_bf16 v[8:11], v[156:159], v[192:195], v[8:11]
	v_mfma_f32_16x16x32_bf16 v[4:7], v[160:163], v[192:195], v[4:7]
	v_mfma_f32_16x16x32_bf16 v[0:3], v[164:167], v[192:195], v[0:3]
	s_waitcnt lgkmcnt(0)
	v_mfma_f32_16x16x32_bf16 v[32:35], v[134:137], v[200:203], v[32:35]
	v_mfma_f32_16x16x32_bf16 v[24:27], v[156:159], v[200:203], v[24:27]
	v_mfma_f32_16x16x32_bf16 v[20:23], v[160:163], v[200:203], v[20:23]
	v_mfma_f32_16x16x32_bf16 v[12:15], v[164:167], v[200:203], v[12:15]
	s_setprio 0
	s_and_b64 vcc, exec, s[52:53]
	s_cbranch_vccnz .Lgt4_last
	s_add_i32 s36, s43, 1
	s_cmp_lg_u32 s43, 2
	s_cselect_b32 s43, s36, 0
	s_add_i32 s36, s41, 1
	s_cmp_lg_u32 s41, 2
	s_cselect_b32 s41, s36, 0
	s_add_i32 s35, s35, 1
	s_add_u32 s48, s48, 0x2000
	s_addc_u32 s49, s49, 0
	s_add_u32 s50, s50, 0x4000
	s_addc_u32 s51, s51, 0
	s_cmp_eq_u32 s35, 32
	s_waitcnt vmcnt(6)
	s_barrier
	s_branch .LBB0_1354

; template <int EPI>
; __device__ __forceinline__ void gemm_phase(const u16* __restrict__ A0, int nksA, size_t sA, const u16* __restrict__ B0, int nksB, size_t sB,
;                                            int K, int nM, int nN, int nbatch, const EpiArgs ea, char* smem, int bid, int nblk) {
;     ...
;     for (int kk = 0; kk < nk; ++kk) {
;       const bool more = kk + 2 < nk;
;       if (more) GSTAGE(kk + 2, nbuf);
;       bf16x8 Bl[4], At[8];
;       {
;         const int bb = sb0 + buf * 8192, ab = sa0 + buf * 16384;
;         asm volatile(
;             "ds_read_b128 %0, %12\n\tds_read_b128 %1, %12 offset:1024\n\tds_read_b128 %2, %12 offset:2048\n\tds_read_b128 %3, %12 offset:3072\n\t"
;             "ds_read_b128 %4, %13\n\tds_read_b128 %5, %13 offset:1024\n\tds_read_b128 %6, %13 offset:2048\n\tds_read_b128 %7, %13 offset:3072\n\t"
;             "ds_read_b128 %8, %13 offset:4096\n\tds_read_b128 %9, %13 offset:5120\n\tds_read_b128 %10, %13 offset:6144\n\tds_read_b128 %11, %13 offset:7168\n\t"
;             "s_waitcnt lgkmcnt(4)"
;             : "=&v"(Bl[0]), "=&v"(Bl[1]), "=&v"(Bl[2]), "=&v"(Bl[3]), "=&v"(At[0]), "=&v"(At[1]), "=&v"(At[2]), "=&v"(At[3]),
;               "=&v"(At[4]), "=&v"(At[5]), "=&v"(At[6]), "=&v"(At[7])
;             : "v"(bb), "v"(ab)
;             : "memory");
;       }
.LBB0_1501:
	v_lshl_add_u32 v139, s58, 13, v145
	v_lshl_add_u32 v140, s58, 14, v143
	ds_read_b128 v[158:161], v139
	ds_read_b128 v[162:165], v139 offset:1024
	ds_read_b128 v[166:169], v139 offset:2048
	ds_read_b128 v[170:173], v139 offset:3072
	ds_read_b128 v[174:177], v140
	ds_read_b128 v[178:181], v140 offset:1024
	ds_read_b128 v[182:185], v140 offset:2048
	ds_read_b128 v[186:189], v140 offset:3072
	ds_read_b128 v[190:193], v140 offset:4096
	ds_read_b128 v[194:197], v140 offset:5120
	ds_read_b128 v[200:203], v140 offset:6144
	ds_read_b128 v[204:207], v140 offset:7168
	s_cbranch_vccnz .Lgd4_skip
	v_readfirstlane_b32 s93, v128
	v_add_u32_e32 v245, 0x1000, v128
	v_add_u32_e32 v246, 0x2000, v128
	v_add_u32_e32 v247, 0x3000, v128
	s_lshl_b32 s92, s43, 14
	s_add_u32 s92, s92, s93
	s_add_u32 s94, s50, 0x31b8000
	s_addc_u32 s95, s51, 0
	s_mov_b32 m0, s92
	s_add_u32 s100, s48, 0x784000
	s_addc_u32 s101, s49, 0
	global_load_lds_dwordx4 v128, s[94:95]
	s_add_u32 m0, s92, 0x1000
	s_lshl_b32 s98, s43, 13
	global_load_lds_dwordx4 v245, s[94:95]
	s_add_u32 m0, s92, 0x2000
	s_add_u32 s98, s98, s93
	global_load_lds_dwordx4 v246, s[94:95]
	s_add_u32 m0, s92, 0x3000
	s_add_u32 s98, s98, 0xc000
	global_load_lds_dwordx4 v247, s[94:95]
	s_mov_b32 m0, s98
	s_nop 0
	global_load_lds_dwordx4 v128, s[100:101]
	s_add_u32 m0, s98, 0x1000
	s_nop 0
	global_load_lds_dwordx4 v245, s[100:101]
.Lgd4_skip:
	s_waitcnt lgkmcnt(7)
	s_setprio 1
	v_mfma_f32_16x16x32_bf16 v[124:127], v[158:161], v[174:177], v[124:127]
	v_mfma_f32_16x16x32_bf16 v[120:123], v[162:165], v[174:177], v[120:123]
	v_mfma_f32_16x16x32_bf16 v[116:119], v[166:169], v[174:177], v[116:119]
	v_mfma_f32_16x16x32_bf16 v[112:115], v[170:173], v[174:177], v[112:115]
	s_waitcnt lgkmcnt(6)
	v_mfma_f32_16x16x32_bf16 v[108:111], v[158:161], v[178:181], v[108:111]
	v_mfma_f32_16x16x32_bf16 v[104:107], v[162:165], v[178:181], v[104:107]
	v_mfma_f32_16x16x32_bf16 v[100:103], v[166:169], v[178:181], v[100:103]
	v_mfma_f32_16x16x32_bf16 v[96:99], v[170:173], v[178:181], v[96:99]
	s_waitcnt lgkmcnt(5)
	v_mfma_f32_16x16x32_bf16 v[92:95], v[158:161], v[182:185], v[92:95]
	v_mfma_f32_16x16x32_bf16 v[88:91], v[162:165], v[182:185], v[88:91]
	v_mfma_f32_16x16x32_bf16 v[84:87], v[166:169], v[182:185], v[84:87]
	v_mfma_f32_16x16x32_bf16 v[80:83], v[170:173], v[182:185], v[80:83]
	s_waitcnt lgkmcnt(4)
	v_mfma_f32_16x16x32_bf16 v[76:79], v[158:161], v[186:189], v[76:79]
	v_mfma_f32_16x16x32_bf16 v[72:75], v[162:165], v[186:189], v[72:75]
	v_mfma_f32_16x16x32_bf16 v[68:71], v[166:169], v[186:189], v[68:71]
	v_mfma_f32_16x16x32_bf16 v[64:67], v[170:173], v[186:189], v[64:67]
	s_waitcnt lgkmcnt(3)
	s_nop 0
	v_mfma_f32_16x16x32_bf16 v[60:63], v[158:161], v[190:193], v[60:63]
	v_mfma_f32_16x16x32_bf16 v[56:59], v[162:165], v[190:193], v[56:59]
	v_mfma_f32_16x16x32_bf16 v[52:55], v[166:169], v[190:193], v[52:55]
	v_mfma_f32_16x16x32_bf16 v[48:51], v[170:173], v[190:193], v[48:51]
	s_waitcnt lgkmcnt(2)
	v_mfma_f32_16x16x32_bf16 v[44:47], v[158:161], v[194:197], v[44:47]
	v_mfma_f32_16x16x32_bf16 v[40:43], v[162:165], v[194:197], v[40:43]
	v_mfma_f32_16x16x32_bf16 v[36:39], v[166:169], v[194:197], v[36:39]
	v_mfma_f32_16x16x32_bf16 v[32:35], v[170:173], v[194:197], v[32:35]
	s_waitcnt lgkmcnt(1)
	v_mfma_f32_16x16x32_bf16 v[20:23], v[158:161], v[200:203], v[20:23]
	v_mfma_f32_16x16x32_bf16 v[16:19], v[162:165], v[200:203], v[16:19]
	v_mfma_f32_16x16x32_bf16 v[4:7], v[166:169], v[200:203], v[4:7]
	v_mfma_f32_16x16x32_bf16 v[0:3], v[170:173], v[200:203], v[0:3]
	s_waitcnt lgkmcnt(0)
	v_mfma_f32_16x16x32_bf16 v[24:27], v[158:161], v[204:207], v[24:27]
	v_mfma_f32_16x16x32_bf16 v[28:31], v[162:165], v[204:207], v[28:31]
	v_mfma_f32_16x16x32_bf16 v[8:11], v[166:169], v[204:207], v[8:11]
	v_mfma_f32_16x16x32_bf16 v[12:15], v[170:173], v[204:207], v[12:15]
	s_setprio 0
	s_and_b64 vcc, exec, s[52:53]
	s_cbranch_vccnz .Lgt5_last
	s_add_i32 s44, s58, 1
	s_cmp_lg_u32 s58, 2
	s_cselect_b32 s58, s44, 0
	s_add_i32 s44, s43, 1
	s_cmp_lg_u32 s43, 2
	s_cselect_b32 s43, s44, 0
	s_add_i32 s41, s41, 1
	s_add_u32 s48, s48, 0x2000
	s_addc_u32 s49, s49, 0
	s_add_u32 s50, s50, 0x4000
	s_addc_u32 s51, s51, 0
	s_cmp_eq_u32 s41, 32
	s_waitcnt vmcnt(6)
	s_barrier
	s_branch .LBB0_1499

; template <int EPI>
; __device__ __forceinline__ void gemm_phase(const u16* __restrict__ A0, int nksA, size_t sA, const u16* __restrict__ B0, int nksB, size_t sB,
;                                            int K, int nM, int nN, int nbatch, const EpiArgs ea, char* smem, int bid, int nblk) {
;     ...
;     for (int kk = 0; kk < nk; ++kk) {
;       const bool more = kk + 2 < nk;
;       if (more) GSTAGE(kk + 2, nbuf);
;       bf16x8 Bl[4], At[8];
;       {
;         const int bb = sb0 + buf * 8192, ab = sa0 + buf * 16384;
;         asm volatile(
;             "ds_read_b128 %0, %12\n\tds_read_b128 %1, %12 offset:1024\n\tds_read_b128 %2, %12 offset:2048\n\tds_read_b128 %3, %12 offset:3072\n\t"
;             "ds_read_b128 %4, %13\n\tds_read_b128 %5, %13 offset:1024\n\tds_read_b128 %6, %13 offset:2048\n\tds_read_b128 %7, %13 offset:3072\n\t"
;             "ds_read_b128 %8, %13 offset:4096\n\tds_read_b128 %9, %13 offset:5120\n\tds_read_b128 %10, %13 offset:6144\n\tds_read_b128 %11, %13 offset:7168\n\t"
;             "s_waitcnt lgkmcnt(4)"
;             : "=&v"(Bl[0]), "=&v"(Bl[1]), "=&v"(Bl[2]), "=&v"(Bl[3]), "=&v"(At[0]), "=&v"(At[1]), "=&v"(At[2]), "=&v"(At[3]),
;               "=&v"(At[4]), "=&v"(At[5]), "=&v"(At[6]), "=&v"(At[7])
;             : "v"(bb), "v"(ab)
;             : "memory");
;       }
.LBB0_1574:
	v_lshl_add_u32 v138, s53, 13, v143
	v_lshl_add_u32 v139, s53, 14, v142
	ds_read_b128 v[134:137], v138
	ds_read_b128 v[156:159], v138 offset:1024
	ds_read_b128 v[160:163], v138 offset:2048
	ds_read_b128 v[164:167], v138 offset:3072
	ds_read_b128 v[168:171], v139
	ds_read_b128 v[172:175], v139 offset:1024
	ds_read_b128 v[176:179], v139 offset:2048
	ds_read_b128 v[180:183], v139 offset:3072
	ds_read_b128 v[184:187], v139 offset:4096
	ds_read_b128 v[188:191], v139 offset:5120
	ds_read_b128 v[192:195], v139 offset:6144
	ds_read_b128 v[200:203], v139 offset:7168
	s_cbranch_vccnz .Lgd5_skip
	v_readfirstlane_b32 s93, v128
	v_add_u32_e32 v245, 0x1000, v128
	v_add_u32_e32 v246, 0x2000, v128
	v_add_u32_e32 v247, 0x3000, v128
	s_lshl_b32 s92, s52, 14
	s_add_u32 s92, s92, s93
	s_add_u32 s94, s38, 0xe1bc000
	s_addc_u32 s95, s39, 0
	s_mov_b32 m0, s92
	s_add_u32 s100, s36, 0x1d84000
	s_addc_u32 s101, s37, 0
	global_load_lds_dwordx4 v128, s[94:95]
	s_add_u32 m0, s92, 0x1000
	s_lshl_b32 s98, s52, 13
	global_load_lds_dwordx4 v245, s[94:95]
	s_add_u32 m0, s92, 0x2000
	s_add_u32 s98, s98, s93
	global_load_lds_dwordx4 v246, s[94:95]
	s_add_u32 m0, s92, 0x3000
	s_add_u32 s98, s98, 0xc000
	global_load_lds_dwordx4 v247, s[94:95]
	s_mov_b32 m0, s98
	s_nop 0
	global_load_lds_dwordx4 v128, s[100:101]
	s_add_u32 m0, s98, 0x1000
	s_nop 0
	global_load_lds_dwordx4 v245, s[100:101]
.Lgd5_skip:
	s_waitcnt lgkmcnt(7)
	s_setprio 1
	v_mfma_f32_16x16x32_bf16 v[124:127], v[134:137], v[168:171], v[124:127]
	v_mfma_f32_16x16x32_bf16 v[120:123], v[156:159], v[168:171], v[120:123]
	v_mfma_f32_16x16x32_bf16 v[116:119], v[160:163], v[168:171], v[116:119]
	v_mfma_f32_16x16x32_bf16 v[112:115], v[164:167], v[168:171], v[112:115]
	s_waitcnt lgkmcnt(6)
	v_mfma_f32_16x16x32_bf16 v[108:111], v[134:137], v[172:175], v[108:111]
	v_mfma_f32_16x16x32_bf16 v[104:107], v[156:159], v[172:175], v[104:107]
	v_mfma_f32_16x16x32_bf16 v[100:103], v[160:163], v[172:175], v[100:103]
	v_mfma_f32_16x16x32_bf16 v[96:99], v[164:167], v[172:175], v[96:99]
	s_waitcnt lgkmcnt(5)
	v_mfma_f32_16x16x32_bf16 v[92:95], v[134:137], v[176:179], v[92:95]
	v_mfma_f32_16x16x32_bf16 v[88:91], v[156:159], v[176:179], v[88:91]
	v_mfma_f32_16x16x32_bf16 v[84:87], v[160:163], v[176:179], v[84:87]
	v_mfma_f32_16x16x32_bf16 v[80:83], v[164:167], v[176:179], v[80:83]
	s_waitcnt lgkmcnt(4)
	v_mfma_f32_16x16x32_bf16 v[76:79], v[134:137], v[180:183], v[76:79]
	v_mfma_f32_16x16x32_bf16 v[72:75], v[156:159], v[180:183], v[72:75]
	v_mfma_f32_16x16x32_bf16 v[68:71], v[160:163], v[180:183], v[68:71]
	v_mfma_f32_16x16x32_bf16 v[64:67], v[164:167], v[180:183], v[64:67]
	s_waitcnt lgkmcnt(3)
	s_nop 0
	v_mfma_f32_16x16x32_bf16 v[60:63], v[134:137], v[184:187], v[60:63]
	v_mfma_f32_16x16x32_bf16 v[56:59], v[156:159], v[184:187], v[56:59]
	v_mfma_f32_16x16x32_bf16 v[52:55], v[160:163], v[184:187], v[52:55]
	v_mfma_f32_16x16x32_bf16 v[48:51], v[164:167], v[184:187], v[48:51]
	s_waitcnt lgkmcnt(2)
	v_mfma_f32_16x16x32_bf16 v[44:47], v[134:137], v[188:191], v[44:47]
	v_mfma_f32_16x16x32_bf16 v[40:43], v[156:159], v[188:191], v[40:43]
	v_mfma_f32_16x16x32_bf16 v[36:39], v[160:163], v[188:191], v[36:39]
	v_mfma_f32_16x16x32_bf16 v[32:35], v[164:167], v[188:191], v[32:35]
	s_waitcnt lgkmcnt(1)
	v_mfma_f32_16x16x32_bf16 v[20:23], v[134:137], v[192:195], v[20:23]
	v_mfma_f32_16x16x32_bf16 v[8:11], v[156:159], v[192:195], v[8:11]
	v_mfma_f32_16x16x32_bf16 v[4:7], v[160:163], v[192:195], v[4:7]
	v_mfma_f32_16x16x32_bf16 v[0:3], v[164:167], v[192:195], v[0:3]
	s_waitcnt lgkmcnt(0)
	v_mfma_f32_16x16x32_bf16 v[28:31], v[134:137], v[200:203], v[28:31]
	v_mfma_f32_16x16x32_bf16 v[24:27], v[156:159], v[200:203], v[24:27]
	v_mfma_f32_16x16x32_bf16 v[16:19], v[160:163], v[200:203], v[16:19]
	v_mfma_f32_16x16x32_bf16 v[12:15], v[164:167], v[200:203], v[12:15]
	s_setprio 0
	s_and_b64 vcc, exec, s[40:41]
	s_cbranch_vccnz .Lgt6_last
	s_add_i32 s40, s53, 1
	s_cmp_lg_u32 s53, 2
	s_cselect_b32 s53, s40, 0
	s_add_i32 s40, s52, 1
	s_cmp_lg_u32 s52, 2
	s_cselect_b32 s52, s40, 0
	s_add_i32 s51, s51, 1
	s_add_u32 s36, s36, 0x2000
	s_addc_u32 s37, s37, 0
	s_add_u32 s38, s38, 0x4000
	s_addc_u32 s39, s39, 0
	s_cmpk_eq_i32 s51, 0x58
	s_waitcnt vmcnt(6)
	s_barrier
	s_branch .LBB0_1572

; template <int EPI>
; __device__ __forceinline__ void gemm_phase(const u16* __restrict__ A0, int nksA, size_t sA, const u16* __restrict__ B0, int nksB, size_t sB,
;                                            int K, int nM, int nN, int nbatch, const EpiArgs ea, char* smem, int bid, int nblk) {
;     ...
;     asm volatile("s_waitcnt vmcnt(0)" ::: "memory");
;     GSTAGE(0, 0);
;     if (nk > 1) { GSTAGE(1, 1); asm volatile("s_waitcnt vmcnt(6)\n\ts_barrier" ::: "memory"); }
;     else { asm volatile("s_waitcnt vmcnt(0)\n\ts_barrier" ::: "memory"); }
;     int buf = 0, nbuf = 2;
; #pragma unroll 1
;     for (int kk = 0; kk < nk; ++kk) {
;       const bool more = kk + 2 < nk;
;       if (more) GSTAGE(kk + 2, nbuf);
;       bf16x8 Bl[4], At[8];
;       {
;         const int bb = sb0 + buf * 8192, ab = sa0 + buf * 16384;
;         asm volatile(
;             "ds_read_b128 %0, %12\n\tds_read_b128 %1, %12 offset:1024\n\tds_read_b128 %2, %12 offset:2048\n\tds_read_b128 %3, %12 offset:3072\n\t"
;             "ds_read_b128 %4, %13\n\tds_read_b128 %5, %13 offset:1024\n\tds_read_b128 %6, %13 offset:2048\n\tds_read_b128 %7, %13 offset:3072\n\t"
;             "ds_read_b128 %8, %13 offset:4096\n\tds_read_b128 %9, %13 offset:5120\n\tds_read_b128 %10, %13 offset:6144\n\tds_read_b128 %11, %13 offset:7168\n\t"
;             "s_waitcnt lgkmcnt(4)"
;             : "=&v"(Bl[0]), "=&v"(Bl[1]), "=&v"(Bl[2]), "=&v"(Bl[3]), "=&v"(At[0]), "=&v"(At[1]), "=&v"(At[2]), "=&v"(At[3]),
;               "=&v"(At[4]), "=&v"(At[5]), "=&v"(At[6]), "=&v"(At[7])
;             : "v"(bb), "v"(ab)
;             : "memory");
;       }
;       __builtin_amdgcn_s_setprio(1);
; #pragma unroll
;       for (int m = 0; m < 4; ++m)
; #pragma unroll
;         for (int n = 0; n < 4; ++n) acc[m][n] = __builtin_amdgcn_mfma_f32_16x16x32_bf16(Bl[n], At[m], acc[m][n], 0, 0, 0);
;       __builtin_amdgcn_sched_barrier(0);
;       asm volatile("s_waitcnt lgkmcnt(0)" : "+v"(At[4]), "+v"(At[5]), "+v"(At[6]), "+v"(At[7]) :: "memory");
;       __builtin_amdgcn_sched_barrier(0);
; #pragma unroll
;       for (int m = 4; m < 8; ++m)
; #pragma unroll
;         for (int n = 0; n < 4; ++n) acc[m][n] = __builtin_amdgcn_mfma_f32_16x16x32_bf16(Bl[n], At[m], acc[m][n], 0, 0, 0);
;       __builtin_amdgcn_s_setprio(0);
;       if (more) asm volatile("s_waitcnt vmcnt(6)\n\ts_barrier" ::: "memory");
.LBB0_1719:
	v_lshl_add_u32 v149, s52, 13, v135
	v_lshl_add_u32 v199, s52, 14, v134
	ds_read_b128 v[150:153], v149
	ds_read_b128 v[154:157], v149 offset:1024
	ds_read_b128 v[158:161], v149 offset:2048
	ds_read_b128 v[162:165], v149 offset:3072
	ds_read_b128 v[166:169], v199
	ds_read_b128 v[170:173], v199 offset:1024
	ds_read_b128 v[174:177], v199 offset:2048
	ds_read_b128 v[178:181], v199 offset:3072
	ds_read_b128 v[182:185], v199 offset:4096
	ds_read_b128 v[186:189], v199 offset:5120
	ds_read_b128 v[190:193], v199 offset:6144
	ds_read_b128 v[194:197], v199 offset:7168
	s_cbranch_vccnz .Lgd6_skip
	v_readfirstlane_b32 s93, v128
	v_add_u32_e32 v245, 0x1000, v128
	v_add_u32_e32 v246, 0x2000, v128
	v_add_u32_e32 v247, 0x3000, v128
	s_lshl_b32 s92, s39, 14
	s_add_u32 s92, s92, s93
	s_add_u32 s94, s42, 0x31b8000
	s_addc_u32 s95, s43, 0
	s_mov_b32 m0, s92
	s_add_u32 s100, s40, 0x2884000
	s_addc_u32 s101, s41, 0
	global_load_lds_dwordx4 v128, s[94:95]
	s_add_u32 m0, s92, 0x1000
	s_lshl_b32 s98, s39, 13
	global_load_lds_dwordx4 v245, s[94:95]
	s_add_u32 m0, s92, 0x2000
	s_add_u32 s98, s98, s93
	global_load_lds_dwordx4 v246, s[94:95]
	s_add_u32 m0, s92, 0x3000
	s_add_u32 s98, s98, 0xc000
	global_load_lds_dwordx4 v247, s[94:95]
	s_mov_b32 m0, s98
	s_nop 0
	global_load_lds_dwordx4 v128, s[100:101]
	s_add_u32 m0, s98, 0x1000
	s_nop 0
	global_load_lds_dwordx4 v245, s[100:101]
.Lgd6_skip:
	s_waitcnt lgkmcnt(7)
	s_setprio 1
	v_mfma_f32_16x16x32_bf16 v[124:127], v[150:153], v[166:169], v[124:127]
	v_mfma_f32_16x16x32_bf16 v[120:123], v[154:157], v[166:169], v[120:123]
	v_mfma_f32_16x16x32_bf16 v[116:119], v[158:161], v[166:169], v[116:119]
	v_mfma_f32_16x16x32_bf16 v[112:115], v[162:165], v[166:169], v[112:115]
	s_waitcnt lgkmcnt(6)
	v_mfma_f32_16x16x32_bf16 v[108:111], v[150:153], v[170:173], v[108:111]
	v_mfma_f32_16x16x32_bf16 v[104:107], v[154:157], v[170:173], v[104:107]
	v_mfma_f32_16x16x32_bf16 v[100:103], v[158:161], v[170:173], v[100:103]
	v_mfma_f32_16x16x32_bf16 v[96:99], v[162:165], v[170:173], v[96:99]
	s_waitcnt lgkmcnt(5)
	v_mfma_f32_16x16x32_bf16 v[92:95], v[150:153], v[174:177], v[92:95]
	v_mfma_f32_16x16x32_bf16 v[88:91], v[154:157], v[174:177], v[88:91]
	v_mfma_f32_16x16x32_bf16 v[84:87], v[158:161], v[174:177], v[84:87]
	v_mfma_f32_16x16x32_bf16 v[80:83], v[162:165], v[174:177], v[80:83]
	s_waitcnt lgkmcnt(4)
	v_mfma_f32_16x16x32_bf16 v[76:79], v[150:153], v[178:181], v[76:79]
	v_mfma_f32_16x16x32_bf16 v[72:75], v[154:157], v[178:181], v[72:75]
	v_mfma_f32_16x16x32_bf16 v[68:71], v[158:161], v[178:181], v[68:71]
	v_mfma_f32_16x16x32_bf16 v[64:67], v[162:165], v[178:181], v[64:67]
	s_waitcnt lgkmcnt(3)
	s_nop 0
	v_mfma_f32_16x16x32_bf16 v[60:63], v[150:153], v[182:185], v[60:63]
	v_mfma_f32_16x16x32_bf16 v[40:43], v[154:157], v[182:185], v[40:43]
	v_mfma_f32_16x16x32_bf16 v[36:39], v[158:161], v[182:185], v[36:39]
	v_mfma_f32_16x16x32_bf16 v[32:35], v[162:165], v[182:185], v[32:35]
	s_waitcnt lgkmcnt(2)
	v_mfma_f32_16x16x32_bf16 v[28:31], v[150:153], v[186:189], v[28:31]
	v_mfma_f32_16x16x32_bf16 v[24:27], v[154:157], v[186:189], v[24:27]
	v_mfma_f32_16x16x32_bf16 v[20:23], v[158:161], v[186:189], v[20:23]
	v_mfma_f32_16x16x32_bf16 v[16:19], v[162:165], v[186:189], v[16:19]
	s_waitcnt lgkmcnt(1)
	v_mfma_f32_16x16x32_bf16 v[12:15], v[150:153], v[190:193], v[12:15]
	v_mfma_f32_16x16x32_bf16 v[8:11], v[154:157], v[190:193], v[8:11]
	v_mfma_f32_16x16x32_bf16 v[4:7], v[158:161], v[190:193], v[4:7]
	v_mfma_f32_16x16x32_bf16 v[0:3], v[162:165], v[190:193], v[0:3]
	s_waitcnt lgkmcnt(0)
	v_mfma_f32_16x16x32_bf16 v[56:59], v[150:153], v[194:197], v[56:59]
	v_mfma_f32_16x16x32_bf16 v[52:55], v[154:157], v[194:197], v[52:55]
	v_mfma_f32_16x16x32_bf16 v[48:51], v[158:161], v[194:197], v[48:51]
	v_mfma_f32_16x16x32_bf16 v[44:47], v[162:165], v[194:197], v[44:47]
	s_setprio 0
	s_and_b64 vcc, exec, s[44:45]
	s_cbranch_vccnz .Lgt7_last
	s_add_i32 s44, s52, 1
	s_cmp_lg_u32 s52, 2
	s_cselect_b32 s52, s44, 0
	s_add_i32 s44, s39, 1
	s_cmp_lg_u32 s39, 2
	s_cselect_b32 s39, s44, 0
	s_add_i32 s37, s37, 1
	s_add_u32 s40, s40, 0x2000
	s_addc_u32 s41, s41, 0
	s_add_u32 s42, s42, 0x4000
	s_addc_u32 s43, s43, 0
	s_cmp_eq_u32 s37, 32
	s_waitcnt vmcnt(6)
	s_barrier
	s_branch .LBB0_1717

; template <int EPI>
; __device__ __forceinline__ void gemm_phase(const u16* __restrict__ A0, int nksA, size_t sA, const u16* __restrict__ B0, int nksB, size_t sB,
;                                            int K, int nM, int nN, int nbatch, const EpiArgs ea, char* smem, int bid, int nblk) {
;     ...
;     asm volatile("s_waitcnt vmcnt(0)" ::: "memory");
;     GSTAGE(0, 0);
;     if (nk > 1) { GSTAGE(1, 1); asm volatile("s_waitcnt vmcnt(6)\n\ts_barrier" ::: "memory"); }
;     else { asm volatile("s_waitcnt vmcnt(0)\n\ts_barrier" ::: "memory"); }
;     int buf = 0, nbuf = 2;
; #pragma unroll 1
;     for (int kk = 0; kk < nk; ++kk) {
;       const bool more = kk + 2 < nk;
;       if (more) GSTAGE(kk + 2, nbuf);
;       bf16x8 Bl[4], At[8];
;       {
;         const int bb = sb0 + buf * 8192, ab = sa0 + buf * 16384;
;         asm volatile(
;             "ds_read_b128 %0, %12\n\tds_read_b128 %1, %12 offset:1024\n\tds_read_b128 %2, %12 offset:2048\n\tds_read_b128 %3, %12 offset:3072\n\t"
;             "ds_read_b128 %4, %13\n\tds_read_b128 %5, %13 offset:1024\n\tds_read_b128 %6, %13 offset:2048\n\tds_read_b128 %7, %13 offset:3072\n\t"
;             "ds_read_b128 %8, %13 offset:4096\n\tds_read_b128 %9, %13 offset:5120\n\tds_read_b128 %10, %13 offset:6144\n\tds_read_b128 %11, %13 offset:7168\n\t"
;             "s_waitcnt lgkmcnt(4)"
;             : "=&v"(Bl[0]), "=&v"(Bl[1]), "=&v"(Bl[2]), "=&v"(Bl[3]), "=&v"(At[0]), "=&v"(At[1]), "=&v"(At[2]), "=&v"(At[3]),
;               "=&v"(At[4]), "=&v"(At[5]), "=&v"(At[6]), "=&v"(At[7])
;             : "v"(bb), "v"(ab)
;             : "memory");
;       }
;       __builtin_amdgcn_s_setprio(1);
; #pragma unroll
;       for (int m = 0; m < 4; ++m)
; #pragma unroll
;         for (int n = 0; n < 4; ++n) acc[m][n] = __builtin_amdgcn_mfma_f32_16x16x32_bf16(Bl[n], At[m], acc[m][n], 0, 0, 0);
;       __builtin_amdgcn_sched_barrier(0);
;       asm volatile("s_waitcnt lgkmcnt(0)" : "+v"(At[4]), "+v"(At[5]), "+v"(At[6]), "+v"(At[7]) :: "memory");
;       __builtin_amdgcn_sched_barrier(0);
; #pragma unroll
;       for (int m = 4; m < 8; ++m)
; #pragma unroll
;         for (int n = 0; n < 4; ++n) acc[m][n] = __builtin_amdgcn_mfma_f32_16x16x32_bf16(Bl[n], At[m], acc[m][n], 0, 0, 0);
;       __builtin_amdgcn_s_setprio(0);
;       if (more) asm volatile("s_waitcnt vmcnt(6)\n\ts_barrier" ::: "memory");
.LBB0_1873:
	v_lshl_add_u32 v138, s51, 13, v143
	v_lshl_add_u32 v139, s51, 14, v142
	ds_read_b128 v[134:137], v138
	ds_read_b128 v[156:159], v138 offset:1024
	ds_read_b128 v[160:163], v138 offset:2048
	ds_read_b128 v[164:167], v138 offset:3072
	ds_read_b128 v[168:171], v139
	ds_read_b128 v[172:175], v139 offset:1024
	ds_read_b128 v[176:179], v139 offset:2048
	ds_read_b128 v[180:183], v139 offset:3072
	ds_read_b128 v[184:187], v139 offset:4096
	ds_read_b128 v[188:191], v139 offset:5120
	ds_read_b128 v[192:195], v139 offset:6144
	ds_read_b128 v[200:203], v139 offset:7168
	s_cbranch_vccnz .Lgd7_skip
	v_readfirstlane_b32 s93, v128
	v_add_u32_e32 v245, 0x1000, v128
	v_add_u32_e32 v246, 0x2000, v128
	v_add_u32_e32 v247, 0x3000, v128
	s_lshl_b32 s92, s39, 14
	s_add_u32 s92, s92, s93
	s_add_u32 s94, s42, 0x31b8000
	s_addc_u32 s95, s43, 0
	s_mov_b32 m0, s92
	s_add_u32 s100, s40, 0x2e84000
	s_addc_u32 s101, s41, 0
	global_load_lds_dwordx4 v128, s[94:95]
	s_add_u32 m0, s92, 0x1000
	s_lshl_b32 s98, s39, 13
	global_load_lds_dwordx4 v245, s[94:95]
	s_add_u32 m0, s92, 0x2000
	s_add_u32 s98, s98, s93
	global_load_lds_dwordx4 v246, s[94:95]
	s_add_u32 m0, s92, 0x3000
	s_add_u32 s98, s98, 0xc000
	global_load_lds_dwordx4 v247, s[94:95]
	s_mov_b32 m0, s98
	s_nop 0
	global_load_lds_dwordx4 v128, s[100:101]
	s_add_u32 m0, s98, 0x1000
	s_nop 0
	global_load_lds_dwordx4 v245, s[100:101]
.Lgd7_skip:
	s_waitcnt lgkmcnt(7)
	s_setprio 1
	v_mfma_f32_16x16x32_bf16 v[124:127], v[134:137], v[168:171], v[124:127]
	v_mfma_f32_16x16x32_bf16 v[120:123], v[156:159], v[168:171], v[120:123]
	v_mfma_f32_16x16x32_bf16 v[116:119], v[160:163], v[168:171], v[116:119]
	v_mfma_f32_16x16x32_bf16 v[112:115], v[164:167], v[168:171], v[112:115]
	s_waitcnt lgkmcnt(6)
	v_mfma_f32_16x16x32_bf16 v[108:111], v[134:137], v[172:175], v[108:111]
	v_mfma_f32_16x16x32_bf16 v[104:107], v[156:159], v[172:175], v[104:107]
	v_mfma_f32_16x16x32_bf16 v[100:103], v[160:163], v[172:175], v[100:103]
	v_mfma_f32_16x16x32_bf16 v[96:99], v[164:167], v[172:175], v[96:99]
	s_waitcnt lgkmcnt(5)
	v_mfma_f32_16x16x32_bf16 v[92:95], v[134:137], v[176:179], v[92:95]
	v_mfma_f32_16x16x32_bf16 v[88:91], v[156:159], v[176:179], v[88:91]
	v_mfma_f32_16x16x32_bf16 v[84:87], v[160:163], v[176:179], v[84:87]
	v_mfma_f32_16x16x32_bf16 v[80:83], v[164:167], v[176:179], v[80:83]
	s_waitcnt lgkmcnt(4)
	v_mfma_f32_16x16x32_bf16 v[76:79], v[134:137], v[180:183], v[76:79]
	v_mfma_f32_16x16x32_bf16 v[72:75], v[156:159], v[180:183], v[72:75]
	v_mfma_f32_16x16x32_bf16 v[68:71], v[160:163], v[180:183], v[68:71]
	v_mfma_f32_16x16x32_bf16 v[64:67], v[164:167], v[180:183], v[64:67]
	s_waitcnt lgkmcnt(3)
	s_nop 0
	v_mfma_f32_16x16x32_bf16 v[60:63], v[134:137], v[184:187], v[60:63]
	v_mfma_f32_16x16x32_bf16 v[56:59], v[156:159], v[184:187], v[56:59]
	v_mfma_f32_16x16x32_bf16 v[52:55], v[160:163], v[184:187], v[52:55]
	v_mfma_f32_16x16x32_bf16 v[48:51], v[164:167], v[184:187], v[48:51]
	s_waitcnt lgkmcnt(2)
	v_mfma_f32_16x16x32_bf16 v[44:47], v[134:137], v[188:191], v[44:47]
	v_mfma_f32_16x16x32_bf16 v[40:43], v[156:159], v[188:191], v[40:43]
	v_mfma_f32_16x16x32_bf16 v[36:39], v[160:163], v[188:191], v[36:39]
	v_mfma_f32_16x16x32_bf16 v[32:35], v[164:167], v[188:191], v[32:35]
	s_waitcnt lgkmcnt(1)
	v_mfma_f32_16x16x32_bf16 v[20:23], v[134:137], v[192:195], v[20:23]
	v_mfma_f32_16x16x32_bf16 v[8:11], v[156:159], v[192:195], v[8:11]
	v_mfma_f32_16x16x32_bf16 v[4:7], v[160:163], v[192:195], v[4:7]
	v_mfma_f32_16x16x32_bf16 v[0:3], v[164:167], v[192:195], v[0:3]
	s_waitcnt lgkmcnt(0)
	v_mfma_f32_16x16x32_bf16 v[28:31], v[134:137], v[200:203], v[28:31]
	v_mfma_f32_16x16x32_bf16 v[24:27], v[156:159], v[200:203], v[24:27]
	v_mfma_f32_16x16x32_bf16 v[16:19], v[160:163], v[200:203], v[16:19]
	v_mfma_f32_16x16x32_bf16 v[12:15], v[164:167], v[200:203], v[12:15]
	s_setprio 0
	s_and_b64 vcc, exec, s[44:45]
	s_cbranch_vccnz .Lgt8_last
	s_add_i32 s44, s51, 1
	s_cmp_lg_u32 s51, 2
	s_cselect_b32 s51, s44, 0
	s_add_i32 s44, s39, 1
	s_cmp_lg_u32 s39, 2
	s_cselect_b32 s39, s44, 0
	s_add_i32 s37, s37, 1
	s_add_u32 s40, s40, 0x2000
	s_addc_u32 s41, s41, 0
	s_add_u32 s42, s42, 0x4000
	s_addc_u32 s43, s43, 0
	s_cmp_eq_u32 s37, 32
	s_waitcnt vmcnt(6)
	s_barrier
	s_branch .LBB0_1871

; template <int EPI>
; __device__ __forceinline__ void gemm_phase(const u16* __restrict__ A0, int nksA, size_t sA, const u16* __restrict__ B0, int nksB, size_t sB,
;                                            int K, int nM, int nN, int nbatch, const EpiArgs ea, char* smem, int bid, int nblk) {
;     ...
;     asm volatile("s_waitcnt vmcnt(0)" ::: "memory");
;     GSTAGE(0, 0);
;     if (nk > 1) { GSTAGE(1, 1); asm volatile("s_waitcnt vmcnt(6)\n\ts_barrier" ::: "memory"); }
;     else { asm volatile("s_waitcnt vmcnt(0)\n\ts_barrier" ::: "memory"); }
;     int buf = 0, nbuf = 2;
; #pragma unroll 1
;     for (int kk = 0; kk < nk; ++kk) {
;       const bool more = kk + 2 < nk;
;       if (more) GSTAGE(kk + 2, nbuf);
;       bf16x8 Bl[4], At[8];
;       {
;         const int bb = sb0 + buf * 8192, ab = sa0 + buf * 16384;
;         asm volatile(
;             "ds_read_b128 %0, %12\n\tds_read_b128 %1, %12 offset:1024\n\tds_read_b128 %2, %12 offset:2048\n\tds_read_b128 %3, %12 offset:3072\n\t"
;             "ds_read_b128 %4, %13\n\tds_read_b128 %5, %13 offset:1024\n\tds_read_b128 %6, %13 offset:2048\n\tds_read_b128 %7, %13 offset:3072\n\t"
;             "ds_read_b128 %8, %13 offset:4096\n\tds_read_b128 %9, %13 offset:5120\n\tds_read_b128 %10, %13 offset:6144\n\tds_read_b128 %11, %13 offset:7168\n\t"
;             "s_waitcnt lgkmcnt(4)"
;             : "=&v"(Bl[0]), "=&v"(Bl[1]), "=&v"(Bl[2]), "=&v"(Bl[3]), "=&v"(At[0]), "=&v"(At[1]), "=&v"(At[2]), "=&v"(At[3]),
;               "=&v"(At[4]), "=&v"(At[5]), "=&v"(At[6]), "=&v"(At[7])
;             : "v"(bb), "v"(ab)
;             : "memory");
;       }
;       __builtin_amdgcn_s_setprio(1);
; #pragma unroll
;       for (int m = 0; m < 4; ++m)
; #pragma unroll
;         for (int n = 0; n < 4; ++n) acc[m][n] = __builtin_amdgcn_mfma_f32_16x16x32_bf16(Bl[n], At[m], acc[m][n], 0, 0, 0);
;       __builtin_amdgcn_sched_barrier(0);
;       asm volatile("s_waitcnt lgkmcnt(0)" : "+v"(At[4]), "+v"(At[5]), "+v"(At[6]), "+v"(At[7]) :: "memory");
;       __builtin_amdgcn_sched_barrier(0);
; #pragma unroll
;       for (int m = 4; m < 8; ++m)
; #pragma unroll
;         for (int n = 0; n < 4; ++n) acc[m][n] = __builtin_amdgcn_mfma_f32_16x16x32_bf16(Bl[n], At[m], acc[m][n], 0, 0, 0);
;       __builtin_amdgcn_s_setprio(0);
;       if (more) asm volatile("s_waitcnt vmcnt(6)\n\ts_barrier" ::: "memory");
.LBB0_2018:
	v_lshl_add_u32 v139, s54, 13, v145
	v_lshl_add_u32 v140, s54, 14, v143
	ds_read_b128 v[158:161], v139
	ds_read_b128 v[162:165], v139 offset:1024
	ds_read_b128 v[166:169], v139 offset:2048
	ds_read_b128 v[170:173], v139 offset:3072
	ds_read_b128 v[174:177], v140
	ds_read_b128 v[178:181], v140 offset:1024
	ds_read_b128 v[182:185], v140 offset:2048
	ds_read_b128 v[186:189], v140 offset:3072
	ds_read_b128 v[190:193], v140 offset:4096
	ds_read_b128 v[194:197], v140 offset:5120
	ds_read_b128 v[200:203], v140 offset:6144
	ds_read_b128 v[204:207], v140 offset:7168
	s_cbranch_vccnz .Lgd8_skip
	v_readfirstlane_b32 s93, v128
	v_add_u32_e32 v245, 0x1000, v128
	v_add_u32_e32 v246, 0x2000, v128
	v_add_u32_e32 v247, 0x3000, v128
	s_lshl_b32 s92, s43, 14
	s_add_u32 s92, s92, s93
	s_add_u32 s94, s46, 0x31b8000
	s_addc_u32 s95, s47, 0
	s_mov_b32 m0, s92
	s_add_u32 s100, s44, 0x1284000
	s_addc_u32 s101, s45, 0
	global_load_lds_dwordx4 v128, s[94:95]
	s_add_u32 m0, s92, 0x1000
	s_lshl_b32 s98, s43, 13
	global_load_lds_dwordx4 v245, s[94:95]
	s_add_u32 m0, s92, 0x2000
	s_add_u32 s98, s98, s93
	global_load_lds_dwordx4 v246, s[94:95]
	s_add_u32 m0, s92, 0x3000
	s_add_u32 s98, s98, 0xc000
	global_load_lds_dwordx4 v247, s[94:95]
	s_mov_b32 m0, s98
	s_nop 0
	global_load_lds_dwordx4 v128, s[100:101]
	s_add_u32 m0, s98, 0x1000
	s_nop 0
	global_load_lds_dwordx4 v245, s[100:101]
.Lgd8_skip:
	s_waitcnt lgkmcnt(7)
	s_setprio 1
	v_mfma_f32_16x16x32_bf16 v[124:127], v[158:161], v[174:177], v[124:127]
	v_mfma_f32_16x16x32_bf16 v[120:123], v[162:165], v[174:177], v[120:123]
	v_mfma_f32_16x16x32_bf16 v[116:119], v[166:169], v[174:177], v[116:119]
	v_mfma_f32_16x16x32_bf16 v[112:115], v[170:173], v[174:177], v[112:115]
	s_waitcnt lgkmcnt(6)
	v_mfma_f32_16x16x32_bf16 v[108:111], v[158:161], v[178:181], v[108:111]
	v_mfma_f32_16x16x32_bf16 v[104:107], v[162:165], v[178:181], v[104:107]
	v_mfma_f32_16x16x32_bf16 v[100:103], v[166:169], v[178:181], v[100:103]
	v_mfma_f32_16x16x32_bf16 v[96:99], v[170:173], v[178:181], v[96:99]
	s_waitcnt lgkmcnt(5)
	v_mfma_f32_16x16x32_bf16 v[92:95], v[158:161], v[182:185], v[92:95]
	v_mfma_f32_16x16x32_bf16 v[88:91], v[162:165], v[182:185], v[88:91]
	v_mfma_f32_16x16x32_bf16 v[84:87], v[166:169], v[182:185], v[84:87]
	v_mfma_f32_16x16x32_bf16 v[80:83], v[170:173], v[182:185], v[80:83]
	s_waitcnt lgkmcnt(4)
	v_mfma_f32_16x16x32_bf16 v[76:79], v[158:161], v[186:189], v[76:79]
	v_mfma_f32_16x16x32_bf16 v[72:75], v[162:165], v[186:189], v[72:75]
	v_mfma_f32_16x16x32_bf16 v[68:71], v[166:169], v[186:189], v[68:71]
	v_mfma_f32_16x16x32_bf16 v[64:67], v[170:173], v[186:189], v[64:67]
	s_waitcnt lgkmcnt(3)
	s_nop 0
	v_mfma_f32_16x16x32_bf16 v[60:63], v[158:161], v[190:193], v[60:63]
	v_mfma_f32_16x16x32_bf16 v[56:59], v[162:165], v[190:193], v[56:59]
	v_mfma_f32_16x16x32_bf16 v[52:55], v[166:169], v[190:193], v[52:55]
	v_mfma_f32_16x16x32_bf16 v[48:51], v[170:173], v[190:193], v[48:51]
	s_waitcnt lgkmcnt(2)
	v_mfma_f32_16x16x32_bf16 v[44:47], v[158:161], v[194:197], v[44:47]
	v_mfma_f32_16x16x32_bf16 v[40:43], v[162:165], v[194:197], v[40:43]
	v_mfma_f32_16x16x32_bf16 v[36:39], v[166:169], v[194:197], v[36:39]
	v_mfma_f32_16x16x32_bf16 v[32:35], v[170:173], v[194:197], v[32:35]
	s_waitcnt lgkmcnt(1)
	v_mfma_f32_16x16x32_bf16 v[20:23], v[158:161], v[200:203], v[20:23]
	v_mfma_f32_16x16x32_bf16 v[16:19], v[162:165], v[200:203], v[16:19]
	v_mfma_f32_16x16x32_bf16 v[4:7], v[166:169], v[200:203], v[4:7]
	v_mfma_f32_16x16x32_bf16 v[0:3], v[170:173], v[200:203], v[0:3]
	s_waitcnt lgkmcnt(0)
	v_mfma_f32_16x16x32_bf16 v[24:27], v[158:161], v[204:207], v[24:27]
	v_mfma_f32_16x16x32_bf16 v[28:31], v[162:165], v[204:207], v[28:31]
	v_mfma_f32_16x16x32_bf16 v[8:11], v[166:169], v[204:207], v[8:11]
	v_mfma_f32_16x16x32_bf16 v[12:15], v[170:173], v[204:207], v[12:15]
	s_setprio 0
	s_and_b64 vcc, exec, s[48:49]
	s_cbranch_vccnz .Lgt9_last
	s_add_i32 s48, s54, 1
	s_cmp_lg_u32 s54, 2
	s_cselect_b32 s54, s48, 0
	s_add_i32 s48, s43, 1
	s_cmp_lg_u32 s43, 2
	s_cselect_b32 s43, s48, 0
	s_add_i32 s41, s41, 1
	s_add_u32 s44, s44, 0x2000
	s_addc_u32 s45, s45, 0
	s_add_u32 s46, s46, 0x4000
	s_addc_u32 s47, s47, 0
	s_cmp_eq_u32 s41, 32
	s_waitcnt vmcnt(6)
	s_barrier
	s_branch .LBB0_2016

; template <int EPI>
; __device__ __forceinline__ void gemm_phase(const u16* __restrict__ A0, int nksA, size_t sA, const u16* __restrict__ B0, int nksB, size_t sB,
;                                            int K, int nM, int nN, int nbatch, const EpiArgs ea, char* smem, int bid, int nblk) {
;     ...
;     asm volatile("s_waitcnt vmcnt(0)" ::: "memory");
;     GSTAGE(0, 0);
;     if (nk > 1) { GSTAGE(1, 1); asm volatile("s_waitcnt vmcnt(6)\n\ts_barrier" ::: "memory"); }
;     else { asm volatile("s_waitcnt vmcnt(0)\n\ts_barrier" ::: "memory"); }
;     int buf = 0, nbuf = 2;
; #pragma unroll 1
;     for (int kk = 0; kk < nk; ++kk) {
;       const bool more = kk + 2 < nk;
;       if (more) GSTAGE(kk + 2, nbuf);
;       bf16x8 Bl[4], At[8];
;       {
;         const int bb = sb0 + buf * 8192, ab = sa0 + buf * 16384;
;         asm volatile(
;             "ds_read_b128 %0, %12\n\tds_read_b128 %1, %12 offset:1024\n\tds_read_b128 %2, %12 offset:2048\n\tds_read_b128 %3, %12 offset:3072\n\t"
;             "ds_read_b128 %4, %13\n\tds_read_b128 %5, %13 offset:1024\n\tds_read_b128 %6, %13 offset:2048\n\tds_read_b128 %7, %13 offset:3072\n\t"
;             "ds_read_b128 %8, %13 offset:4096\n\tds_read_b128 %9, %13 offset:5120\n\tds_read_b128 %10, %13 offset:6144\n\tds_read_b128 %11, %13 offset:7168\n\t"
;             "s_waitcnt lgkmcnt(4)"
;             : "=&v"(Bl[0]), "=&v"(Bl[1]), "=&v"(Bl[2]), "=&v"(Bl[3]), "=&v"(At[0]), "=&v"(At[1]), "=&v"(At[2]), "=&v"(At[3]),
;               "=&v"(At[4]), "=&v"(At[5]), "=&v"(At[6]), "=&v"(At[7])
;             : "v"(bb), "v"(ab)
;             : "memory");
;       }
;       __builtin_amdgcn_s_setprio(1);
; #pragma unroll
;       for (int m = 0; m < 4; ++m)
; #pragma unroll
;         for (int n = 0; n < 4; ++n) acc[m][n] = __builtin_amdgcn_mfma_f32_16x16x32_bf16(Bl[n], At[m], acc[m][n], 0, 0, 0);
;       __builtin_amdgcn_sched_barrier(0);
;       asm volatile("s_waitcnt lgkmcnt(0)" : "+v"(At[4]), "+v"(At[5]), "+v"(At[6]), "+v"(At[7]) :: "memory");
;       __builtin_amdgcn_sched_barrier(0);
; #pragma unroll
;       for (int m = 4; m < 8; ++m)
; #pragma unroll
;         for (int n = 0; n < 4; ++n) acc[m][n] = __builtin_amdgcn_mfma_f32_16x16x32_bf16(Bl[n], At[m], acc[m][n], 0, 0, 0);
;       __builtin_amdgcn_s_setprio(0);
;       if (more) asm volatile("s_waitcnt vmcnt(6)\n\ts_barrier" ::: "memory");
.LBB0_2091:
	v_lshl_add_u32 v138, s49, 13, v143
	v_lshl_add_u32 v139, s49, 14, v142
	ds_read_b128 v[134:137], v138
	ds_read_b128 v[156:159], v138 offset:1024
	ds_read_b128 v[160:163], v138 offset:2048
	ds_read_b128 v[164:167], v138 offset:3072
	ds_read_b128 v[168:171], v139
	ds_read_b128 v[172:175], v139 offset:1024
	ds_read_b128 v[176:179], v139 offset:2048
	ds_read_b128 v[180:183], v139 offset:3072
	ds_read_b128 v[184:187], v139 offset:4096
	ds_read_b128 v[188:191], v139 offset:5120
	ds_read_b128 v[192:195], v139 offset:6144
	ds_read_b128 v[200:203], v139 offset:7168
	s_cbranch_vccnz .Lgd9_skip
	v_readfirstlane_b32 s93, v128
	v_add_u32_e32 v245, 0x1000, v128
	v_add_u32_e32 v246, 0x2000, v128
	v_add_u32_e32 v247, 0x3000, v128
	s_lshl_b32 s92, s48, 14
	s_add_u32 s92, s92, s93
	s_add_u32 s94, s38, 0xe1bc000
	s_addc_u32 s95, s39, 0
	s_mov_b32 m0, s92
	s_add_u32 s100, s36, 0x2304000
	s_addc_u32 s101, s37, 0
	global_load_lds_dwordx4 v128, s[94:95]
	s_add_u32 m0, s92, 0x1000
	s_lshl_b32 s98, s48, 13
	global_load_lds_dwordx4 v245, s[94:95]
	s_add_u32 m0, s92, 0x2000
	s_add_u32 s98, s98, s93
	global_load_lds_dwordx4 v246, s[94:95]
	s_add_u32 m0, s92, 0x3000
	s_add_u32 s98, s98, 0xc000
	global_load_lds_dwordx4 v247, s[94:95]
	s_mov_b32 m0, s98
	s_nop 0
	global_load_lds_dwordx4 v128, s[100:101]
	s_add_u32 m0, s98, 0x1000
	s_nop 0
	global_load_lds_dwordx4 v245, s[100:101]
.Lgd9_skip:
	s_waitcnt lgkmcnt(7)
	s_setprio 1
	v_mfma_f32_16x16x32_bf16 v[124:127], v[134:137], v[168:171], v[124:127]
	v_mfma_f32_16x16x32_bf16 v[120:123], v[156:159], v[168:171], v[120:123]
	v_mfma_f32_16x16x32_bf16 v[116:119], v[160:163], v[168:171], v[116:119]
	v_mfma_f32_16x16x32_bf16 v[112:115], v[164:167], v[168:171], v[112:115]
	s_waitcnt lgkmcnt(6)
	v_mfma_f32_16x16x32_bf16 v[108:111], v[134:137], v[172:175], v[108:111]
	v_mfma_f32_16x16x32_bf16 v[104:107], v[156:159], v[172:175], v[104:107]
	v_mfma_f32_16x16x32_bf16 v[100:103], v[160:163], v[172:175], v[100:103]
	v_mfma_f32_16x16x32_bf16 v[96:99], v[164:167], v[172:175], v[96:99]
	s_waitcnt lgkmcnt(5)
	v_mfma_f32_16x16x32_bf16 v[92:95], v[134:137], v[176:179], v[92:95]
	v_mfma_f32_16x16x32_bf16 v[88:91], v[156:159], v[176:179], v[88:91]
	v_mfma_f32_16x16x32_bf16 v[84:87], v[160:163], v[176:179], v[84:87]
	v_mfma_f32_16x16x32_bf16 v[80:83], v[164:167], v[176:179], v[80:83]
	s_waitcnt lgkmcnt(4)
	v_mfma_f32_16x16x32_bf16 v[76:79], v[134:137], v[180:183], v[76:79]
	v_mfma_f32_16x16x32_bf16 v[72:75], v[156:159], v[180:183], v[72:75]
	v_mfma_f32_16x16x32_bf16 v[68:71], v[160:163], v[180:183], v[68:71]
	v_mfma_f32_16x16x32_bf16 v[64:67], v[164:167], v[180:183], v[64:67]
	s_waitcnt lgkmcnt(3)
	s_nop 0
	v_mfma_f32_16x16x32_bf16 v[60:63], v[134:137], v[184:187], v[60:63]
	v_mfma_f32_16x16x32_bf16 v[56:59], v[156:159], v[184:187], v[56:59]
	v_mfma_f32_16x16x32_bf16 v[52:55], v[160:163], v[184:187], v[52:55]
	v_mfma_f32_16x16x32_bf16 v[48:51], v[164:167], v[184:187], v[48:51]
	s_waitcnt lgkmcnt(2)
	v_mfma_f32_16x16x32_bf16 v[44:47], v[134:137], v[188:191], v[44:47]
	v_mfma_f32_16x16x32_bf16 v[40:43], v[156:159], v[188:191], v[40:43]
	v_mfma_f32_16x16x32_bf16 v[36:39], v[160:163], v[188:191], v[36:39]
	v_mfma_f32_16x16x32_bf16 v[32:35], v[164:167], v[188:191], v[32:35]
	s_waitcnt lgkmcnt(1)
	v_mfma_f32_16x16x32_bf16 v[20:23], v[134:137], v[192:195], v[20:23]
	v_mfma_f32_16x16x32_bf16 v[8:11], v[156:159], v[192:195], v[8:11]
	v_mfma_f32_16x16x32_bf16 v[4:7], v[160:163], v[192:195], v[4:7]
	v_mfma_f32_16x16x32_bf16 v[0:3], v[164:167], v[192:195], v[0:3]
	s_waitcnt lgkmcnt(0)
	v_mfma_f32_16x16x32_bf16 v[28:31], v[134:137], v[200:203], v[28:31]
	v_mfma_f32_16x16x32_bf16 v[24:27], v[156:159], v[200:203], v[24:27]
	v_mfma_f32_16x16x32_bf16 v[16:19], v[160:163], v[200:203], v[16:19]
	v_mfma_f32_16x16x32_bf16 v[12:15], v[164:167], v[200:203], v[12:15]
	s_setprio 0
	s_and_b64 vcc, exec, s[40:41]
	s_cbranch_vccnz .Lgt10_last
	s_add_i32 s40, s49, 1
	s_cmp_lg_u32 s49, 2
	s_cselect_b32 s49, s40, 0
	s_add_i32 s40, s48, 1
	s_cmp_lg_u32 s48, 2
	s_cselect_b32 s48, s40, 0
	s_add_i32 s47, s47, 1
	s_add_u32 s36, s36, 0x2000
	s_addc_u32 s37, s37, 0
	s_add_u32 s38, s38, 0x4000
	s_addc_u32 s39, s39, 0
	s_cmpk_eq_i32 s47, 0x58
	s_waitcnt vmcnt(6)
	s_barrier
	s_branch .LBB0_2089
